# previous version but the single static s_setprio 1 goes to waves 0-3 (older half) instead of waves 4-7; no priority changes inside the scans
# speedup vs baseline: 1.0074x; 1.0039x over previous
; #define LAS __attribute__((address_space(3)))
; __global__ void __launch_bounds__(NTHREADS, 2) fwd_megakernel(Args args) {
;     extern __shared__ __attribute__((aligned(16))) unsigned char lds_raw[];
;     LAS unsigned char* lds = (LAS unsigned char*)lds_raw;
;     cg::grid_group grid = cg::this_grid();
;     const int bid = blockIdx.x, G = gridDim.x;
_Z14fwd_megakernel4Args:
	v_readfirstlane_b32 s3, v0
	s_nop 3
	s_bfe_u32 s3, s3, 0x40006
	s_cmp_lt_u32 s3, 4
	s_cbranch_scc0 .Lprio_skip
	s_setprio 1
